# P2: fifth pooling units assigned only to conv-first workgroups
# baseline (speedup 1.0000x reference)
; __device__ __forceinline__ void mixer_phase(const Params& p, LAS unsigned char* lds) {
;     ...
;     for (int u = bx; u < 1024; u += G) {
;         const int tt = u >> 2, g = u & 3, b = tt >> 5, t0 = (tt & 31) * 64, grow0 = b * T + t0, w = 2 << g;
;         POOL_LOADW(g);
;         u32x4 cp[3];
; #pragma unroll
;         for (int i = 0; i < 3; ++i) cp[i] = pq[i];
;         if (u + G < 1024) POOL_PREFETCH(u + G);
.LBB0_291:
	s_add_i32 s76, s77, s3
	s_cmpk_gt_i32 s76, 0x3ff
	s_cselect_b64 s[74:75], -1, 0
	s_cmp_lg_u32 s3, 0x100
	s_cbranch_scc1 .Lmy_p2std
	s_cmp_lt_u32 s2, 48
	s_movk_i32 s98, 0x3ff
	s_cselect_b32 s98, 0x1ff, s98
	s_cmp_gt_i32 s76, s98
	s_cselect_b64 s[74:75], -1, 0
	s_sub_u32 s100, s2, 48
	s_cbranch_scc1 .Lmy_p2std
	s_bitcmp1_b32 s2, 3
	s_cbranch_scc1 .Lmy_p2std
	s_lshr_b32 s100, s100, 4
	s_lshl_b32 s100, s100, 3
	s_and_b32 s98, s2, 7
	s_add_i32 s100, s100, s98
	s_cmp_lt_u32 s100, 0x60
	s_cbranch_scc0 .Lmy_p2std
	s_cmp_eq_u32 s99, 0
	s_cbranch_scc0 .Lmy_p2fin
	s_cmp_gt_i32 s76, 0x3ff
	s_cbranch_scc0 .Lmy_p2std
	s_mov_b32 s99, 1
	s_add_i32 s76, s100, 0x200
	s_cmp_lt_u32 s100, 48
	s_cbranch_scc1 .Lmy_p2set
	s_add_i32 s76, s100, 0x2d0
